# scan4 + stagger: waves 4-7 s_sleep 12 after the per-pair barrier in the three attention DMA loops
# speedup vs baseline: 1.0232x; 1.0001x over previous
; #define ATT_ISSUE2(p_, st_) do { LAS unsigned char* sp_ = lds + (st_) * STG2; const int ta_ = dual ? (p_) : 2 * (p_), tb_ = dual ? (p_) : 2 * (p_) + 1; ATT_ISSUE1(u, ta_, sp_); ATT_ISSUEM(ta_, sp_ + 2 * STAGEB); \
;         if (dual || tb_ < u.ntiles) { ATT_ISSUE1(ub, tb_, sp_ + STAGEB); ATT_ISSUEM(tb_, sp_ + 2 * STAGEB + MSKB); } } while (0)
;     ...
;         const AttnUnit& ub = dual ? u2 : u;
;         const int npairs = dual ? u.ntiles : (u.ntiles + 1) >> 1, p0 = dual ? T0 : T0 >> 1;
;         ATT_ISSUE2(p0, p0 & 1);
;         for (int p = p0; p < npairs; ++p) {
;             asm volatile("s_waitcnt vmcnt(0)" ::: "memory");
;             __builtin_amdgcn_s_barrier(); asm volatile("" ::: "memory");
;             if (p + 1 < npairs) ATT_ISSUE2(p + 1, (p + 1) & 1);
.LBB0_579:
	s_add_i32 s27, s2, 1
	s_waitcnt vmcnt(0)
	s_barrier
	v_readlane_b32 s98, v254, 11
	s_nop 3
	s_cmp_lt_u32 s98, 4
	s_cbranch_scc1 .Lstag_579
	s_sleep 12
.Lstag_579:
	s_cmp_ge_u32 s27, s8
	s_cselect_b64 s[6:7], -1, 0
	s_and_b64 vcc, exec, s[6:7]
	s_cbranch_vccnz .LBB0_582
	s_bitcmp1_b32 s27, 0
	s_cselect_b32 s1, 0x10400, 0
	s_ashr_i32 s5, s4, 31
	s_lshl_b64 s[28:29], s[4:5], 12
	s_add_i32 s1, s1, 0
	s_add_i32 s34, s74, 3
	s_or_b64 s[28:29], s[28:29], s[10:11]
	s_add_u32 s30, s56, s28
	s_addc_u32 s31, s57, s29
	s_add_u32 s28, s49, s28
	s_addc_u32 s29, s50, s29
	v_lshl_add_u64 v[148:149], s[30:31], 0, v[174:175]
	s_add_i32 s3, s1, s61
	v_lshl_add_u64 v[148:149], v[148:149], 0, v[2:3]
	s_mov_b32 m0, s3
	s_add_i32 s5, s1, s63
	global_load_lds_dwordx4 v[148:149], off
	v_lshl_add_u64 v[148:149], s[28:29], 0, v[174:175]
	v_lshl_add_u64 v[148:149], v[148:149], 0, v[176:177]
	s_add_i32 m0, s3, 0x4000
	s_nop 0
	global_load_lds_dwordx4 v[148:149], off
	v_lshl_add_u64 v[148:149], s[30:31], 0, v[178:179]
	v_lshl_add_u64 v[148:149], v[148:149], 0, v[180:181]
	s_mov_b32 m0, s5
	s_nop 0
	global_load_lds_dwordx4 v[148:149], off
	v_lshl_add_u64 v[148:149], s[28:29], 0, v[178:179]
	v_lshl_add_u64 v[148:149], v[148:149], 0, v[182:183]
	s_add_i32 m0, s5, 0x4000
	s_cmp_ge_u32 s34, s75
	global_load_lds_dwordx4 v[148:149], off
	s_cbranch_scc1 .LBB0_582
	s_ashr_i32 s1, s0, 31
	s_lshl_b64 s[28:29], s[0:1], 12
	s_or_b64 s[28:29], s[28:29], s[10:11]
	s_add_u32 s30, s56, s28
	s_addc_u32 s31, s57, s29
	s_add_u32 s28, s49, s28
	v_lshl_add_u64 v[148:149], s[30:31], 0, v[174:175]
	s_addc_u32 s29, s50, s29
	v_lshl_add_u64 v[148:149], v[148:149], 0, v[2:3]
	s_add_i32 m0, s3, 0x8000
	s_nop 0
	global_load_lds_dwordx4 v[148:149], off
	v_lshl_add_u64 v[148:149], s[28:29], 0, v[174:175]
	v_lshl_add_u64 v[148:149], v[148:149], 0, v[176:177]
	s_add_i32 m0, s3, 0xc000
	s_nop 0
	global_load_lds_dwordx4 v[148:149], off
	v_lshl_add_u64 v[148:149], s[30:31], 0, v[178:179]
	v_lshl_add_u64 v[148:149], v[148:149], 0, v[180:181]
	s_add_i32 m0, s5, 0x8000
	s_nop 0
	global_load_lds_dwordx4 v[148:149], off
	v_lshl_add_u64 v[148:149], s[28:29], 0, v[178:179]
	v_lshl_add_u64 v[148:149], v[148:149], 0, v[182:183]
	s_add_i32 m0, s5, 0xc000
	s_nop 0
	global_load_lds_dwordx4 v[148:149], off

; #define ATT_ISSUE2(p_, st_) do { LAS unsigned char* sp_ = lds + (st_) * STG2; const int ta_ = dual ? (p_) : 2 * (p_), tb_ = dual ? (p_) : 2 * (p_) + 1; ATT_ISSUE1(u, ta_, sp_); ATT_ISSUEM(ta_, sp_ + 2 * STAGEB); \
;         if (dual || tb_ < u.ntiles) { ATT_ISSUE1(ub, tb_, sp_ + STAGEB); ATT_ISSUEM(tb_, sp_ + 2 * STAGEB + MSKB); } } while (0)
;     ...
;         const AttnUnit& ub = dual ? u2 : u;
;         const int npairs = dual ? u.ntiles : (u.ntiles + 1) >> 1, p0 = dual ? T0 : T0 >> 1;
;         ATT_ISSUE2(p0, p0 & 1);
;         for (int p = p0; p < npairs; ++p) {
;             asm volatile("s_waitcnt vmcnt(0)" ::: "memory");
;             __builtin_amdgcn_s_barrier(); asm volatile("" ::: "memory");
;             if (p + 1 < npairs) ATT_ISSUE2(p + 1, (p + 1) & 1);
.LBB0_2104:
	s_waitcnt vmcnt(0)
	s_barrier
	v_readlane_b32 s98, v254, 11
	s_nop 3
	s_cmp_lt_u32 s98, 4
	s_cbranch_scc1 .Lstag_2104
	s_sleep 12
.Lstag_2104:
	s_add_i32 s80, s4, 1
	s_cmp_ge_i32 s80, s71
	s_cbranch_scc1 .LBB0_2110
	s_bitcmp1_b32 s80, 0
	s_cselect_b32 s0, 0x10400, 0
	s_add_i32 s5, s0, 0
	s_sub_i32 s0, s72, 64
	s_lshl_b64 s[6:7], s[0:1], 10
	s_or_b64 s[6:7], s[6:7], s[78:79]
	s_add_u32 s8, s74, s6
	s_addc_u32 s9, s75, s7
	s_add_u32 s10, s76, s6
	s_addc_u32 s11, s77, s7
	v_lshl_add_u64 v[82:83], s[8:9], 0, v[16:17]
	s_add_i32 s0, s5, s96
	v_lshl_add_u64 v[82:83], v[82:83], 0, v[2:3]
	s_mov_b32 m0, s0
	s_add_i32 s6, s5, s89
	global_load_lds_dwordx4 v[82:83], off
	v_lshl_add_u64 v[82:83], s[10:11], 0, v[16:17]
	v_lshl_add_u64 v[82:83], v[82:83], 0, v[144:145]
	s_add_i32 m0, s0, 0x4000
	s_and_b64 vcc, exec, s[2:3]
	global_load_lds_dwordx4 v[82:83], off
	v_lshl_add_u64 v[82:83], s[8:9], 0, v[146:147]
	v_lshl_add_u64 v[82:83], v[82:83], 0, v[148:149]
	s_mov_b32 m0, s6
	s_nop 0
	global_load_lds_dwordx4 v[82:83], off
	v_lshl_add_u64 v[82:83], s[10:11], 0, v[146:147]
	v_lshl_add_u64 v[82:83], v[82:83], 0, v[150:151]
	s_add_i32 m0, s6, 0x4000
	s_nop 0
	global_load_lds_dwordx4 v[82:83], off
	s_cbranch_vccnz .LBB0_2107
	v_add_u32_e32 v82, -8, v154
	s_add_i32 s7, s5, s93
	v_ashrrev_i32_e32 v83, 31, v82
	s_add_i32 m0, s7, 0x10000
	v_lshl_add_u64 v[82:83], v[152:153], 0, v[82:83]
	global_load_lds_dword v[82:83], off

; #define ATT_ISSUE2(p_, st_) do { LAS unsigned char* sp_ = lds + (st_) * STG2; const int ta_ = dual ? (p_) : 2 * (p_), tb_ = dual ? (p_) : 2 * (p_) + 1; ATT_ISSUE1(u, ta_, sp_); ATT_ISSUEM(ta_, sp_ + 2 * STAGEB); \
;         if (dual || tb_ < u.ntiles) { ATT_ISSUE1(ub, tb_, sp_ + STAGEB); ATT_ISSUEM(tb_, sp_ + 2 * STAGEB + MSKB); } } while (0)
;     ...
;         const AttnUnit& ub = dual ? u2 : u;
;         const int npairs = dual ? u.ntiles : (u.ntiles + 1) >> 1, p0 = dual ? T0 : T0 >> 1;
;         ATT_ISSUE2(p0, p0 & 1);
;         for (int p = p0; p < npairs; ++p) {
;             asm volatile("s_waitcnt vmcnt(0)" ::: "memory");
;             __builtin_amdgcn_s_barrier(); asm volatile("" ::: "memory");
;             if (p + 1 < npairs) ATT_ISSUE2(p + 1, (p + 1) & 1);
.LBB0_3301:
	s_add_i32 s96, s97, 1
	s_waitcnt vmcnt(0)
	s_barrier
	v_readlane_b32 s98, v254, 11
	s_nop 3
	s_cmp_lt_u32 s98, 4
	s_cbranch_scc1 .Lstag_3301
	s_sleep 12
.Lstag_3301:
	s_cmp_ge_i32 s96, s21
	s_cselect_b64 s[46:47], -1, 0
	s_and_b64 vcc, exec, s[46:47]
	s_cbranch_vccnz .LBB0_3316
	s_mov_b64 s[48:49], -1
	s_and_b64 vcc, exec, s[26:27]
	s_cbranch_vccz .LBB0_3306
	s_cmp_gt_u32 s97, 62
	s_mov_b64 s[4:5], s[38:39]
	s_mov_b64 s[2:3], s[36:37]
	s_cbranch_scc1 .LBB0_3305
	s_add_i32 s2, s90, s95
	s_or_b32 s2, s34, s2
	s_mov_b32 s3, s35
	s_lshl_b64 s[4:5], s[2:3], 8
	s_add_u32 s2, s62, s4
	s_addc_u32 s3, s63, s5
	s_add_u32 s4, s70, s4
	s_addc_u32 s5, s71, s5

; __global__ void __launch_bounds__(NTHR, 2) mega(Args args) {
	.amdhsa_kernel _Z4mega4Args
		.amdhsa_group_segment_fixed_size 0
		.amdhsa_private_segment_fixed_size 0
		.amdhsa_kernarg_size 520
		.amdhsa_user_sgpr_count 2
		.amdhsa_user_sgpr_dispatch_ptr 0
		.amdhsa_user_sgpr_queue_ptr 0
		.amdhsa_user_sgpr_kernarg_segment_ptr 1
		.amdhsa_user_sgpr_dispatch_id 0
		.amdhsa_user_sgpr_kernarg_preload_length 0
		.amdhsa_user_sgpr_kernarg_preload_offset 0
		.amdhsa_user_sgpr_private_segment_size 0
		.amdhsa_uses_dynamic_stack 0
		.amdhsa_enable_private_segment 0
		.amdhsa_system_sgpr_workgroup_id_x 1
		.amdhsa_system_sgpr_workgroup_id_y 0
		.amdhsa_system_sgpr_workgroup_id_z 0
		.amdhsa_system_sgpr_workgroup_info 0
		.amdhsa_system_vgpr_workitem_id 0
		.amdhsa_next_free_vgpr 256
		.amdhsa_next_free_sgpr 102
		.amdhsa_accum_offset 256
		.amdhsa_reserve_vcc 1
		.amdhsa_float_round_mode_32 0
		.amdhsa_float_round_mode_16_64 0
		.amdhsa_float_denorm_mode_32 3
		.amdhsa_float_denorm_mode_16_64 3
		.amdhsa_dx10_clamp 1
		.amdhsa_ieee_mode 1
		.amdhsa_fp16_overflow 0
		.amdhsa_tg_split 0
		.amdhsa_exception_fp_ieee_invalid_op 0
		.amdhsa_exception_fp_denorm_src 0
		.amdhsa_exception_fp_ieee_div_zero 0
		.amdhsa_exception_fp_ieee_overflow 0
		.amdhsa_exception_fp_ieee_underflow 0
		.amdhsa_exception_fp_ieee_inexact 0
		.amdhsa_exception_int_div_zero 0
	.end_amdhsa_kernel

; __global__ void __launch_bounds__(NTHR, 2) mega(Args args) {
amdhsa.kernels:
  - .agpr_count:     0
    .args:
      - .offset:         0
        .size:           264
        .value_kind:     by_value
      - .offset:         264
        .size:           4
        .value_kind:     hidden_block_count_x
      - .offset:         268
        .size:           4
        .value_kind:     hidden_block_count_y
      - .offset:         272
        .size:           4
        .value_kind:     hidden_block_count_z
      - .offset:         276
        .size:           2
        .value_kind:     hidden_group_size_x
      - .offset:         278
        .size:           2
        .value_kind:     hidden_group_size_y
      - .offset:         280
        .size:           2
        .value_kind:     hidden_group_size_z
      - .offset:         282
        .size:           2
        .value_kind:     hidden_remainder_x
      - .offset:         284
        .size:           2
        .value_kind:     hidden_remainder_y
      - .offset:         286
        .size:           2
        .value_kind:     hidden_remainder_z
      - .offset:         304
        .size:           8
        .value_kind:     hidden_global_offset_x
      - .offset:         312
        .size:           8
        .value_kind:     hidden_global_offset_y
      - .offset:         320
        .size:           8
        .value_kind:     hidden_global_offset_z
      - .offset:         328
        .size:           2
        .value_kind:     hidden_grid_dims
      - .offset:         384
        .size:           4
        .value_kind:     hidden_dynamic_lds_size
    .group_segment_fixed_size: 0
    .kernarg_segment_align: 8
    .kernarg_segment_size: 520
    .language:       OpenCL C
    .language_version:
      - 2
      - 0
    .max_flat_workgroup_size: 512
    .name:           _Z4mega4Args
    .private_segment_fixed_size: 0
    .sgpr_count:     108
    .sgpr_spill_count: 155
    .symbol:         _Z4mega4Args.kd
    .uniform_work_group_size: 1
    .uses_dynamic_stack: false
    .vgpr_count:     256
    .vgpr_spill_count: 0
    .wavefront_size: 64
